# GEMM K-loops: LDS-DMA pieces addressed scalar base + 32-bit lane offset (16 v_lshl_add_u64 per trip removed from the load segments); on the 4+4 staging
# baseline (speedup 1.0000x reference)
.LBB0_206:
	s_add_u32 s10, s22, 0xfffc0080
	s_addc_u32 s11, s23, -1
	s_add_i32 s12, 0, 0x10000
	s_cmp_eq_u32 vcc_hi, 12
	s_cselect_b32 s61, s9, s11
	s_cselect_b32 s60, s31, s10
	v_add_u32_e32 v152, s12, v157
	s_cselect_b32 s43, s41, vcc_lo
	s_cselect_b32 s42, s53, s55
	s_add_i32 s13, 0, 0x14000
	ds_read_b128 v[140:143], v152
	ds_read_b128 v[144:147], v152 offset:1024
	ds_read_b128 v[148:151], v152 offset:2048
	ds_read_b128 v[160:163], v152 offset:3072
	v_add_u32_e32 v152, s13, v157
	ds_read_b128 v[164:167], v152
	ds_read_b128 v[168:171], v152 offset:1024
	ds_read_b128 v[172:175], v152 offset:2048
	ds_read_b128 v[176:179], v152 offset:3072
	s_add_u32 s10, s22, 0xfffc0000
	s_addc_u32 s11, s23, -1
	s_mov_b32 m0, s83
	s_nop 0
	global_load_lds_dwordx4 v136, s[10:11]
	s_mov_b32 m0, s95
	s_nop 0
	global_load_lds_dwordx4 v138, s[10:11]
	s_add_i32 m0, s75, 0xc000
	ds_read_b128 v[180:183], v159
	ds_read_b128 v[184:187], v159 offset:1024
	ds_read_b128 v[188:191], v159 offset:2048
	ds_read_b128 v[206:209], v159 offset:3072
	ds_read_b128 v[210:213], v159 offset:4096
	ds_read_b128 v[214:217], v159 offset:5120
	ds_read_b128 v[218:221], v159 offset:6144
	ds_read_b128 v[222:225], v159 offset:7168
	global_load_lds_dwordx4 v136, s[22:23]
	s_add_i32 m0, s75, 0xe000
	s_nop 0
	global_load_lds_dwordx4 v138, s[22:23]
	s_waitcnt vmcnt(8)
	s_waitcnt lgkmcnt(0)
	s_barrier
	s_setprio 1
	s_waitcnt lgkmcnt(0)
	v_mfma_f32_16x16x32_bf16 v[124:127], v[140:143], v[180:183], v[124:127]
	v_mfma_f32_16x16x32_bf16 v[120:123], v[148:151], v[180:183], v[120:123]
	v_mfma_f32_16x16x32_bf16 v[108:111], v[140:143], v[188:191], v[108:111]
	v_mfma_f32_16x16x32_bf16 v[104:107], v[148:151], v[188:191], v[104:107]
	v_mfma_f32_16x16x32_bf16 v[92:95], v[140:143], v[210:213], v[92:95]
	v_mfma_f32_16x16x32_bf16 v[88:91], v[148:151], v[210:213], v[88:91]
	v_mfma_f32_16x16x32_bf16 v[76:79], v[140:143], v[218:221], v[76:79]
	v_mfma_f32_16x16x32_bf16 v[72:75], v[148:151], v[218:221], v[72:75]
	v_mfma_f32_16x16x32_bf16 v[124:127], v[144:147], v[184:187], v[124:127]
	v_mfma_f32_16x16x32_bf16 v[120:123], v[160:163], v[184:187], v[120:123]
	v_mfma_f32_16x16x32_bf16 v[108:111], v[144:147], v[206:209], v[108:111]
	v_mfma_f32_16x16x32_bf16 v[104:107], v[160:163], v[206:209], v[104:107]
	v_mfma_f32_16x16x32_bf16 v[92:95], v[144:147], v[214:217], v[92:95]
	v_mfma_f32_16x16x32_bf16 v[88:91], v[160:163], v[214:217], v[88:91]
	v_mfma_f32_16x16x32_bf16 v[76:79], v[144:147], v[222:225], v[76:79]
	v_mfma_f32_16x16x32_bf16 v[72:75], v[160:163], v[222:225], v[72:75]
	s_setprio 0
	s_setprio 1
	v_mfma_f32_16x16x32_bf16 v[116:119], v[164:167], v[180:183], v[116:119]
	v_mfma_f32_16x16x32_bf16 v[112:115], v[172:175], v[180:183], v[112:115]
	v_mfma_f32_16x16x32_bf16 v[100:103], v[164:167], v[188:191], v[100:103]
	v_mfma_f32_16x16x32_bf16 v[96:99], v[172:175], v[188:191], v[96:99]
	v_mfma_f32_16x16x32_bf16 v[84:87], v[164:167], v[210:213], v[84:87]
	v_mfma_f32_16x16x32_bf16 v[80:83], v[172:175], v[210:213], v[80:83]
	v_mfma_f32_16x16x32_bf16 v[68:71], v[164:167], v[218:221], v[68:71]
	v_mfma_f32_16x16x32_bf16 v[64:67], v[172:175], v[218:221], v[64:67]
	v_mfma_f32_16x16x32_bf16 v[116:119], v[168:171], v[184:187], v[116:119]
	v_mfma_f32_16x16x32_bf16 v[112:115], v[176:179], v[184:187], v[112:115]
	v_mfma_f32_16x16x32_bf16 v[100:103], v[168:171], v[206:209], v[100:103]
	v_mfma_f32_16x16x32_bf16 v[96:99], v[176:179], v[206:209], v[96:99]
	v_mfma_f32_16x16x32_bf16 v[84:87], v[168:171], v[214:217], v[84:87]
	v_mfma_f32_16x16x32_bf16 v[80:83], v[176:179], v[214:217], v[80:83]
	v_mfma_f32_16x16x32_bf16 v[68:71], v[168:171], v[222:225], v[68:71]
	v_mfma_f32_16x16x32_bf16 v[64:67], v[176:179], v[222:225], v[64:67]
	s_setprio 0
	s_barrier
	s_add_i32 s10, s12, s67
	s_mov_b32 m0, s10
	ds_read_b128 v[180:183], v159 offset:16384
	ds_read_b128 v[184:187], v159 offset:17408
	ds_read_b128 v[188:191], v159 offset:18432
	ds_read_b128 v[206:209], v159 offset:19456
	ds_read_b128 v[210:213], v159 offset:20480
	ds_read_b128 v[214:217], v159 offset:21504
	ds_read_b128 v[218:221], v159 offset:22528
	ds_read_b128 v[222:225], v159 offset:23552
	global_load_lds_dwordx4 v192, s[42:43]
	s_add_i32 m0, s10, 0x2000
	s_add_u32 s10, s42, 0x40000
	s_addc_u32 s11, s43, 0
	s_add_i32 s12, s13, s67
	global_load_lds_dwordx4 v132, s[42:43]
	s_mov_b32 m0, s12
	s_nop 0
	global_load_lds_dwordx4 v192, s[10:11]
	s_add_i32 m0, s12, 0x2000
	s_nop 0
	global_load_lds_dwordx4 v132, s[10:11]
	s_waitcnt vmcnt(6)
	s_waitcnt lgkmcnt(0)
	s_barrier
	s_setprio 1
	s_waitcnt lgkmcnt(0)
	v_mfma_f32_16x16x32_bf16 v[60:63], v[140:143], v[180:183], v[60:63]
	v_mfma_f32_16x16x32_bf16 v[56:59], v[148:151], v[180:183], v[56:59]
	v_mfma_f32_16x16x32_bf16 v[44:47], v[140:143], v[188:191], v[44:47]
	v_mfma_f32_16x16x32_bf16 v[40:43], v[148:151], v[188:191], v[40:43]
	v_mfma_f32_16x16x32_bf16 v[28:31], v[140:143], v[210:213], v[28:31]
	v_mfma_f32_16x16x32_bf16 v[24:27], v[148:151], v[210:213], v[24:27]
	v_mfma_f32_16x16x32_bf16 v[12:15], v[140:143], v[218:221], v[12:15]
	v_mfma_f32_16x16x32_bf16 v[8:11], v[148:151], v[218:221], v[8:11]
	v_mfma_f32_16x16x32_bf16 v[60:63], v[144:147], v[184:187], v[60:63]
	v_mfma_f32_16x16x32_bf16 v[56:59], v[160:163], v[184:187], v[56:59]
	v_mfma_f32_16x16x32_bf16 v[44:47], v[144:147], v[206:209], v[44:47]
	v_mfma_f32_16x16x32_bf16 v[40:43], v[160:163], v[206:209], v[40:43]
	v_mfma_f32_16x16x32_bf16 v[28:31], v[144:147], v[214:217], v[28:31]
	v_mfma_f32_16x16x32_bf16 v[24:27], v[160:163], v[214:217], v[24:27]
	v_mfma_f32_16x16x32_bf16 v[12:15], v[144:147], v[222:225], v[12:15]
	v_mfma_f32_16x16x32_bf16 v[8:11], v[160:163], v[222:225], v[8:11]
	s_setprio 0
	s_setprio 1
	v_mfma_f32_16x16x32_bf16 v[52:55], v[164:167], v[180:183], v[52:55]
	v_mfma_f32_16x16x32_bf16 v[48:51], v[172:175], v[180:183], v[48:51]
	v_mfma_f32_16x16x32_bf16 v[36:39], v[164:167], v[188:191], v[36:39]
	v_mfma_f32_16x16x32_bf16 v[32:35], v[172:175], v[188:191], v[32:35]
	v_mfma_f32_16x16x32_bf16 v[20:23], v[164:167], v[210:213], v[20:23]
	v_mfma_f32_16x16x32_bf16 v[16:19], v[172:175], v[210:213], v[16:19]
	v_mfma_f32_16x16x32_bf16 v[4:7], v[164:167], v[218:221], v[4:7]
	v_mfma_f32_16x16x32_bf16 v[0:3], v[172:175], v[218:221], v[0:3]
	v_mfma_f32_16x16x32_bf16 v[52:55], v[168:171], v[184:187], v[52:55]
	v_mfma_f32_16x16x32_bf16 v[48:51], v[176:179], v[184:187], v[48:51]
	v_mfma_f32_16x16x32_bf16 v[36:39], v[168:171], v[206:209], v[36:39]
	v_mfma_f32_16x16x32_bf16 v[32:35], v[176:179], v[206:209], v[32:35]
	v_mfma_f32_16x16x32_bf16 v[20:23], v[168:171], v[214:217], v[20:23]
	v_mfma_f32_16x16x32_bf16 v[16:19], v[176:179], v[214:217], v[16:19]
	v_mfma_f32_16x16x32_bf16 v[4:7], v[168:171], v[222:225], v[4:7]
	v_mfma_f32_16x16x32_bf16 v[0:3], v[176:179], v[222:225], v[0:3]
	s_setprio 0
	s_barrier
	s_add_i32 s12, 0, 0x18000
	s_add_i32 s13, 0, 0x1c000
	v_add_u32_e32 v160, s12, v157
	v_add_u32_e32 v176, s13, v157
	ds_read_b128 v[140:143], v160
	ds_read_b128 v[144:147], v160 offset:1024
	ds_read_b128 v[148:151], v160 offset:2048
	ds_read_b128 v[160:163], v160 offset:3072
	ds_read_b128 v[164:167], v176
	ds_read_b128 v[168:171], v176 offset:1024
	ds_read_b128 v[172:175], v176 offset:2048
	ds_read_b128 v[176:179], v176 offset:3072
	s_mov_b32 m0, s75
	s_nop 0
	global_load_lds_dwordx4 v128, s[60:61]
	s_mov_b32 m0, s78
	s_nop 0
	global_load_lds_dwordx4 v130, s[60:61]
	s_add_u32 s10, s60, 0x40000
	s_addc_u32 s11, s61, 0
	s_mov_b32 m0, s79
	ds_read_b128 v[180:183], v159 offset:32768
	ds_read_b128 v[184:187], v159 offset:33792
	ds_read_b128 v[188:191], v159 offset:34816
	ds_read_b128 v[206:209], v159 offset:35840
	ds_read_b128 v[210:213], v159 offset:36864
	ds_read_b128 v[214:217], v159 offset:37888
	ds_read_b128 v[218:221], v159 offset:38912
	ds_read_b128 v[222:225], v159 offset:39936
	global_load_lds_dwordx4 v128, s[10:11]
	s_mov_b32 m0, s82
	s_nop 0
	global_load_lds_dwordx4 v130, s[10:11]
	s_waitcnt vmcnt(8)
	s_waitcnt lgkmcnt(0)
	s_barrier
	s_setprio 1
	s_waitcnt lgkmcnt(0)
	v_mfma_f32_16x16x32_bf16 v[124:127], v[140:143], v[180:183], v[124:127]
	v_mfma_f32_16x16x32_bf16 v[120:123], v[148:151], v[180:183], v[120:123]
	v_mfma_f32_16x16x32_bf16 v[108:111], v[140:143], v[188:191], v[108:111]
	v_mfma_f32_16x16x32_bf16 v[104:107], v[148:151], v[188:191], v[104:107]
	v_mfma_f32_16x16x32_bf16 v[92:95], v[140:143], v[210:213], v[92:95]
	v_mfma_f32_16x16x32_bf16 v[88:91], v[148:151], v[210:213], v[88:91]
	v_mfma_f32_16x16x32_bf16 v[76:79], v[140:143], v[218:221], v[76:79]
	v_mfma_f32_16x16x32_bf16 v[72:75], v[148:151], v[218:221], v[72:75]
	v_mfma_f32_16x16x32_bf16 v[124:127], v[144:147], v[184:187], v[124:127]
	v_mfma_f32_16x16x32_bf16 v[120:123], v[160:163], v[184:187], v[120:123]
	v_mfma_f32_16x16x32_bf16 v[108:111], v[144:147], v[206:209], v[108:111]
	v_mfma_f32_16x16x32_bf16 v[104:107], v[160:163], v[206:209], v[104:107]
	v_mfma_f32_16x16x32_bf16 v[92:95], v[144:147], v[214:217], v[92:95]
	v_mfma_f32_16x16x32_bf16 v[88:91], v[160:163], v[214:217], v[88:91]
	v_mfma_f32_16x16x32_bf16 v[76:79], v[144:147], v[222:225], v[76:79]
	v_mfma_f32_16x16x32_bf16 v[72:75], v[160:163], v[222:225], v[72:75]
	s_setprio 0
	s_setprio 1
	v_mfma_f32_16x16x32_bf16 v[116:119], v[164:167], v[180:183], v[116:119]
	v_mfma_f32_16x16x32_bf16 v[112:115], v[172:175], v[180:183], v[112:115]
	v_mfma_f32_16x16x32_bf16 v[100:103], v[164:167], v[188:191], v[100:103]
	v_mfma_f32_16x16x32_bf16 v[96:99], v[172:175], v[188:191], v[96:99]
	v_mfma_f32_16x16x32_bf16 v[84:87], v[164:167], v[210:213], v[84:87]
	v_mfma_f32_16x16x32_bf16 v[80:83], v[172:175], v[210:213], v[80:83]
	v_mfma_f32_16x16x32_bf16 v[68:71], v[164:167], v[218:221], v[68:71]
	v_mfma_f32_16x16x32_bf16 v[64:67], v[172:175], v[218:221], v[64:67]
	v_mfma_f32_16x16x32_bf16 v[116:119], v[168:171], v[184:187], v[116:119]
	v_mfma_f32_16x16x32_bf16 v[112:115], v[176:179], v[184:187], v[112:115]
	v_mfma_f32_16x16x32_bf16 v[100:103], v[168:171], v[206:209], v[100:103]
	v_mfma_f32_16x16x32_bf16 v[96:99], v[176:179], v[206:209], v[96:99]
	v_mfma_f32_16x16x32_bf16 v[84:87], v[168:171], v[214:217], v[84:87]
	v_mfma_f32_16x16x32_bf16 v[80:83], v[176:179], v[214:217], v[80:83]
	v_mfma_f32_16x16x32_bf16 v[68:71], v[168:171], v[222:225], v[68:71]
	v_mfma_f32_16x16x32_bf16 v[64:67], v[176:179], v[222:225], v[64:67]
	s_setprio 0
	s_barrier
	s_add_i32 s10, s12, s67
	s_add_i32 m0, s10, 0xffffff80
	ds_read_b128 v[180:183], v159 offset:49152
	ds_read_b128 v[184:187], v159 offset:50176
	ds_read_b128 v[188:191], v159 offset:51200
	ds_read_b128 v[206:209], v159 offset:52224
	ds_read_b128 v[210:213], v159 offset:53248
	ds_read_b128 v[214:217], v159 offset:54272
	ds_read_b128 v[218:221], v159 offset:55296
	ds_read_b128 v[222:225], v159 offset:56320
	global_load_lds_dwordx4 v192, s[42:43] offset:128
	s_add_i32 m0, s10, 0x1f80
	s_add_u32 s10, s42, 0x40080
	s_addc_u32 s11, s43, 0
	s_add_i32 s12, s13, s67
	global_load_lds_dwordx4 v132, s[42:43] offset:128
	s_mov_b32 m0, s12
	s_nop 0
	global_load_lds_dwordx4 v192, s[10:11]
	s_add_i32 m0, s12, 0x2000
	s_nop 0
	global_load_lds_dwordx4 v132, s[10:11]
	s_waitcnt vmcnt(6)
	s_waitcnt lgkmcnt(0)
	s_barrier
	s_setprio 1
	s_waitcnt lgkmcnt(0)
	v_mfma_f32_16x16x32_bf16 v[60:63], v[140:143], v[180:183], v[60:63]
	v_mfma_f32_16x16x32_bf16 v[56:59], v[148:151], v[180:183], v[56:59]
	v_mfma_f32_16x16x32_bf16 v[44:47], v[140:143], v[188:191], v[44:47]
	v_mfma_f32_16x16x32_bf16 v[40:43], v[148:151], v[188:191], v[40:43]
	v_mfma_f32_16x16x32_bf16 v[28:31], v[140:143], v[210:213], v[28:31]
	v_mfma_f32_16x16x32_bf16 v[24:27], v[148:151], v[210:213], v[24:27]
	v_mfma_f32_16x16x32_bf16 v[12:15], v[140:143], v[218:221], v[12:15]
	v_mfma_f32_16x16x32_bf16 v[8:11], v[148:151], v[218:221], v[8:11]
	v_mfma_f32_16x16x32_bf16 v[60:63], v[144:147], v[184:187], v[60:63]
	v_mfma_f32_16x16x32_bf16 v[56:59], v[160:163], v[184:187], v[56:59]
	v_mfma_f32_16x16x32_bf16 v[44:47], v[144:147], v[206:209], v[44:47]
	v_mfma_f32_16x16x32_bf16 v[40:43], v[160:163], v[206:209], v[40:43]
	v_mfma_f32_16x16x32_bf16 v[28:31], v[144:147], v[214:217], v[28:31]
	v_mfma_f32_16x16x32_bf16 v[24:27], v[160:163], v[214:217], v[24:27]
	v_mfma_f32_16x16x32_bf16 v[12:15], v[144:147], v[222:225], v[12:15]
	v_mfma_f32_16x16x32_bf16 v[8:11], v[160:163], v[222:225], v[8:11]
	s_setprio 0
	s_setprio 1
	v_mfma_f32_16x16x32_bf16 v[52:55], v[164:167], v[180:183], v[52:55]
	v_mfma_f32_16x16x32_bf16 v[48:51], v[172:175], v[180:183], v[48:51]
	v_mfma_f32_16x16x32_bf16 v[36:39], v[164:167], v[188:191], v[36:39]
	v_mfma_f32_16x16x32_bf16 v[32:35], v[172:175], v[188:191], v[32:35]
	v_mfma_f32_16x16x32_bf16 v[20:23], v[164:167], v[210:213], v[20:23]
	v_mfma_f32_16x16x32_bf16 v[16:19], v[172:175], v[210:213], v[16:19]
	v_mfma_f32_16x16x32_bf16 v[4:7], v[164:167], v[218:221], v[4:7]
	v_mfma_f32_16x16x32_bf16 v[0:3], v[172:175], v[218:221], v[0:3]
	v_mfma_f32_16x16x32_bf16 v[52:55], v[168:171], v[184:187], v[52:55]
	v_mfma_f32_16x16x32_bf16 v[48:51], v[176:179], v[184:187], v[48:51]
	v_mfma_f32_16x16x32_bf16 v[36:39], v[168:171], v[206:209], v[36:39]
	v_mfma_f32_16x16x32_bf16 v[32:35], v[176:179], v[206:209], v[32:35]
	v_mfma_f32_16x16x32_bf16 v[20:23], v[168:171], v[214:217], v[20:23]
	v_mfma_f32_16x16x32_bf16 v[16:19], v[176:179], v[214:217], v[16:19]
	v_mfma_f32_16x16x32_bf16 v[4:7], v[168:171], v[222:225], v[4:7]
	v_mfma_f32_16x16x32_bf16 v[0:3], v[176:179], v[222:225], v[0:3]
	s_setprio 0
	s_barrier
	s_add_i32 vcc_hi, vcc_hi, 2
	s_add_u32 s22, s22, 0x100
	s_addc_u32 s23, s23, 0
	s_add_u32 s55, s55, 0x100
	s_addc_u32 vcc_lo, vcc_lo, 0
	s_cmp_gt_u32 vcc_hi, 13
	s_cbranch_scc0 .LBB0_206
	s_and_b64 vcc, exec, s[48:49]
	s_cbranch_vccz .LBB0_209
	s_barrier

.LBB0_1039:
	s_add_u32 s10, s60, 0xfffc0080
	s_addc_u32 s11, s61, -1
	s_add_i32 s12, 0, 0x10000
	s_cmp_eq_u32 s96, 12
	s_cselect_b32 s65, s51, s11
	s_cselect_b32 s64, s57, s10
	v_add_u32_e32 v142, s12, v147
	s_cselect_b32 s63, s49, s95
	s_cselect_b32 s62, s82, s83
	s_add_i32 s13, 0, 0x14000
	ds_read_b128 v[138:141], v142
	ds_read_b128 v[150:153], v142 offset:1024
	ds_read_b128 v[154:157], v142 offset:2048
	ds_read_b128 v[158:161], v142 offset:3072
	v_add_u32_e32 v142, s13, v147
	ds_read_b128 v[162:165], v142
	ds_read_b128 v[166:169], v142 offset:1024
	ds_read_b128 v[170:173], v142 offset:2048
	ds_read_b128 v[174:177], v142 offset:3072
	s_add_u32 s10, s60, 0xfffc0000
	s_addc_u32 s11, s61, -1
	s_mov_b32 m0, s66
	s_nop 0
	global_load_lds_dwordx4 v134, s[10:11]
	s_mov_b32 m0, s67
	s_nop 0
	global_load_lds_dwordx4 v136, s[10:11]
	s_add_i32 m0, s8, 0xc000
	ds_read_b128 v[178:181], v149
	ds_read_b128 v[182:185], v149 offset:1024
	ds_read_b128 v[186:189], v149 offset:2048
	ds_read_b128 v[206:209], v149 offset:3072
	ds_read_b128 v[210:213], v149 offset:4096
	ds_read_b128 v[214:217], v149 offset:5120
	ds_read_b128 v[218:221], v149 offset:6144
	ds_read_b128 v[222:225], v149 offset:7168
	global_load_lds_dwordx4 v134, s[60:61]
	s_add_i32 m0, s8, 0xe000
	s_nop 0
	global_load_lds_dwordx4 v136, s[60:61]
	s_waitcnt vmcnt(8)
	s_waitcnt lgkmcnt(0)
	s_barrier
	s_setprio 1
	s_waitcnt lgkmcnt(0)
	v_mfma_f32_16x16x32_bf16 v[124:127], v[138:141], v[178:181], v[124:127]
	v_mfma_f32_16x16x32_bf16 v[120:123], v[154:157], v[178:181], v[120:123]
	v_mfma_f32_16x16x32_bf16 v[108:111], v[138:141], v[186:189], v[108:111]
	v_mfma_f32_16x16x32_bf16 v[104:107], v[154:157], v[186:189], v[104:107]
	v_mfma_f32_16x16x32_bf16 v[92:95], v[138:141], v[210:213], v[92:95]
	v_mfma_f32_16x16x32_bf16 v[88:91], v[154:157], v[210:213], v[88:91]
	v_mfma_f32_16x16x32_bf16 v[76:79], v[138:141], v[218:221], v[76:79]
	v_mfma_f32_16x16x32_bf16 v[72:75], v[154:157], v[218:221], v[72:75]
	v_mfma_f32_16x16x32_bf16 v[124:127], v[150:153], v[182:185], v[124:127]
	v_mfma_f32_16x16x32_bf16 v[120:123], v[158:161], v[182:185], v[120:123]
	v_mfma_f32_16x16x32_bf16 v[108:111], v[150:153], v[206:209], v[108:111]
	v_mfma_f32_16x16x32_bf16 v[104:107], v[158:161], v[206:209], v[104:107]
	v_mfma_f32_16x16x32_bf16 v[92:95], v[150:153], v[214:217], v[92:95]
	v_mfma_f32_16x16x32_bf16 v[88:91], v[158:161], v[214:217], v[88:91]
	v_mfma_f32_16x16x32_bf16 v[76:79], v[150:153], v[222:225], v[76:79]
	v_mfma_f32_16x16x32_bf16 v[72:75], v[158:161], v[222:225], v[72:75]
	s_setprio 0
	s_setprio 1
	v_mfma_f32_16x16x32_bf16 v[116:119], v[162:165], v[178:181], v[116:119]
	v_mfma_f32_16x16x32_bf16 v[112:115], v[170:173], v[178:181], v[112:115]
	v_mfma_f32_16x16x32_bf16 v[100:103], v[162:165], v[186:189], v[100:103]
	v_mfma_f32_16x16x32_bf16 v[96:99], v[170:173], v[186:189], v[96:99]
	v_mfma_f32_16x16x32_bf16 v[84:87], v[162:165], v[210:213], v[84:87]
	v_mfma_f32_16x16x32_bf16 v[80:83], v[170:173], v[210:213], v[80:83]
	v_mfma_f32_16x16x32_bf16 v[68:71], v[162:165], v[218:221], v[68:71]
	v_mfma_f32_16x16x32_bf16 v[64:67], v[170:173], v[218:221], v[64:67]
	v_mfma_f32_16x16x32_bf16 v[116:119], v[166:169], v[182:185], v[116:119]
	v_mfma_f32_16x16x32_bf16 v[112:115], v[174:177], v[182:185], v[112:115]
	v_mfma_f32_16x16x32_bf16 v[100:103], v[166:169], v[206:209], v[100:103]
	v_mfma_f32_16x16x32_bf16 v[96:99], v[174:177], v[206:209], v[96:99]
	v_mfma_f32_16x16x32_bf16 v[84:87], v[166:169], v[214:217], v[84:87]
	v_mfma_f32_16x16x32_bf16 v[80:83], v[174:177], v[214:217], v[80:83]
	v_mfma_f32_16x16x32_bf16 v[68:71], v[166:169], v[222:225], v[68:71]
	v_mfma_f32_16x16x32_bf16 v[64:67], v[174:177], v[222:225], v[64:67]
	s_setprio 0
	s_barrier
	s_add_i32 s10, s12, s7
	s_mov_b32 m0, s10
	ds_read_b128 v[178:181], v149 offset:16384
	ds_read_b128 v[182:185], v149 offset:17408
	ds_read_b128 v[186:189], v149 offset:18432
	ds_read_b128 v[206:209], v149 offset:19456
	ds_read_b128 v[210:213], v149 offset:20480
	ds_read_b128 v[214:217], v149 offset:21504
	ds_read_b128 v[218:221], v149 offset:22528
	ds_read_b128 v[222:225], v149 offset:23552
	global_load_lds_dwordx4 v192, s[62:63]
	s_add_i32 m0, s10, 0x2000
	s_add_u32 s10, s62, 0x40000
	s_addc_u32 s11, s63, 0
	s_add_i32 s12, s13, s7
	global_load_lds_dwordx4 v132, s[62:63]
	s_mov_b32 m0, s12
	s_nop 0
	global_load_lds_dwordx4 v192, s[10:11]
	s_add_i32 m0, s12, 0x2000
	s_nop 0
	global_load_lds_dwordx4 v132, s[10:11]
	s_waitcnt vmcnt(6)
	s_waitcnt lgkmcnt(0)
	s_barrier
	s_setprio 1
	s_waitcnt lgkmcnt(0)
	v_mfma_f32_16x16x32_bf16 v[60:63], v[138:141], v[178:181], v[60:63]
	v_mfma_f32_16x16x32_bf16 v[56:59], v[154:157], v[178:181], v[56:59]
	v_mfma_f32_16x16x32_bf16 v[44:47], v[138:141], v[186:189], v[44:47]
	v_mfma_f32_16x16x32_bf16 v[40:43], v[154:157], v[186:189], v[40:43]
	v_mfma_f32_16x16x32_bf16 v[28:31], v[138:141], v[210:213], v[28:31]
	v_mfma_f32_16x16x32_bf16 v[24:27], v[154:157], v[210:213], v[24:27]
	v_mfma_f32_16x16x32_bf16 v[12:15], v[138:141], v[218:221], v[12:15]
	v_mfma_f32_16x16x32_bf16 v[8:11], v[154:157], v[218:221], v[8:11]
	v_mfma_f32_16x16x32_bf16 v[60:63], v[150:153], v[182:185], v[60:63]
	v_mfma_f32_16x16x32_bf16 v[56:59], v[158:161], v[182:185], v[56:59]
	v_mfma_f32_16x16x32_bf16 v[44:47], v[150:153], v[206:209], v[44:47]
	v_mfma_f32_16x16x32_bf16 v[40:43], v[158:161], v[206:209], v[40:43]
	v_mfma_f32_16x16x32_bf16 v[28:31], v[150:153], v[214:217], v[28:31]
	v_mfma_f32_16x16x32_bf16 v[24:27], v[158:161], v[214:217], v[24:27]
	v_mfma_f32_16x16x32_bf16 v[12:15], v[150:153], v[222:225], v[12:15]
	v_mfma_f32_16x16x32_bf16 v[8:11], v[158:161], v[222:225], v[8:11]
	s_setprio 0
	s_setprio 1
	v_mfma_f32_16x16x32_bf16 v[52:55], v[162:165], v[178:181], v[52:55]
	v_mfma_f32_16x16x32_bf16 v[48:51], v[170:173], v[178:181], v[48:51]
	v_mfma_f32_16x16x32_bf16 v[36:39], v[162:165], v[186:189], v[36:39]
	v_mfma_f32_16x16x32_bf16 v[32:35], v[170:173], v[186:189], v[32:35]
	v_mfma_f32_16x16x32_bf16 v[20:23], v[162:165], v[210:213], v[20:23]
	v_mfma_f32_16x16x32_bf16 v[16:19], v[170:173], v[210:213], v[16:19]
	v_mfma_f32_16x16x32_bf16 v[4:7], v[162:165], v[218:221], v[4:7]
	v_mfma_f32_16x16x32_bf16 v[0:3], v[170:173], v[218:221], v[0:3]
	v_mfma_f32_16x16x32_bf16 v[52:55], v[166:169], v[182:185], v[52:55]
	v_mfma_f32_16x16x32_bf16 v[48:51], v[174:177], v[182:185], v[48:51]
	v_mfma_f32_16x16x32_bf16 v[36:39], v[166:169], v[206:209], v[36:39]
	v_mfma_f32_16x16x32_bf16 v[32:35], v[174:177], v[206:209], v[32:35]
	v_mfma_f32_16x16x32_bf16 v[20:23], v[166:169], v[214:217], v[20:23]
	v_mfma_f32_16x16x32_bf16 v[16:19], v[174:177], v[214:217], v[16:19]
	v_mfma_f32_16x16x32_bf16 v[4:7], v[166:169], v[222:225], v[4:7]
	v_mfma_f32_16x16x32_bf16 v[0:3], v[174:177], v[222:225], v[0:3]
	s_setprio 0
	s_barrier
	s_add_i32 s12, 0, 0x18000
	s_add_i32 s13, 0, 0x1c000
	v_add_u32_e32 v158, s12, v147
	v_add_u32_e32 v174, s13, v147
	ds_read_b128 v[138:141], v158
	ds_read_b128 v[150:153], v158 offset:1024
	ds_read_b128 v[154:157], v158 offset:2048
	ds_read_b128 v[158:161], v158 offset:3072
	ds_read_b128 v[162:165], v174
	ds_read_b128 v[166:169], v174 offset:1024
	ds_read_b128 v[170:173], v174 offset:2048
	ds_read_b128 v[174:177], v174 offset:3072
	s_mov_b32 m0, s8
	s_nop 0
	global_load_lds_dwordx4 v128, s[64:65]
	s_mov_b32 m0, s9
	s_nop 0
	global_load_lds_dwordx4 v130, s[64:65]
	s_add_u32 s10, s64, 0x40000
	s_addc_u32 s11, s65, 0
	s_mov_b32 m0, s26
	ds_read_b128 v[178:181], v149 offset:32768
	ds_read_b128 v[182:185], v149 offset:33792
	ds_read_b128 v[186:189], v149 offset:34816
	ds_read_b128 v[206:209], v149 offset:35840
	ds_read_b128 v[210:213], v149 offset:36864
	ds_read_b128 v[214:217], v149 offset:37888
	ds_read_b128 v[218:221], v149 offset:38912
	ds_read_b128 v[222:225], v149 offset:39936
	global_load_lds_dwordx4 v128, s[10:11]
	s_mov_b32 m0, s59
	s_nop 0
	global_load_lds_dwordx4 v130, s[10:11]
	s_waitcnt vmcnt(8)
	s_waitcnt lgkmcnt(0)
	s_barrier
	s_setprio 1
	s_waitcnt lgkmcnt(0)
	v_mfma_f32_16x16x32_bf16 v[124:127], v[138:141], v[178:181], v[124:127]
	v_mfma_f32_16x16x32_bf16 v[120:123], v[154:157], v[178:181], v[120:123]
	v_mfma_f32_16x16x32_bf16 v[108:111], v[138:141], v[186:189], v[108:111]
	v_mfma_f32_16x16x32_bf16 v[104:107], v[154:157], v[186:189], v[104:107]
	v_mfma_f32_16x16x32_bf16 v[92:95], v[138:141], v[210:213], v[92:95]
	v_mfma_f32_16x16x32_bf16 v[88:91], v[154:157], v[210:213], v[88:91]
	v_mfma_f32_16x16x32_bf16 v[76:79], v[138:141], v[218:221], v[76:79]
	v_mfma_f32_16x16x32_bf16 v[72:75], v[154:157], v[218:221], v[72:75]
	v_mfma_f32_16x16x32_bf16 v[124:127], v[150:153], v[182:185], v[124:127]
	v_mfma_f32_16x16x32_bf16 v[120:123], v[158:161], v[182:185], v[120:123]
	v_mfma_f32_16x16x32_bf16 v[108:111], v[150:153], v[206:209], v[108:111]
	v_mfma_f32_16x16x32_bf16 v[104:107], v[158:161], v[206:209], v[104:107]
	v_mfma_f32_16x16x32_bf16 v[92:95], v[150:153], v[214:217], v[92:95]
	v_mfma_f32_16x16x32_bf16 v[88:91], v[158:161], v[214:217], v[88:91]
	v_mfma_f32_16x16x32_bf16 v[76:79], v[150:153], v[222:225], v[76:79]
	v_mfma_f32_16x16x32_bf16 v[72:75], v[158:161], v[222:225], v[72:75]
	s_setprio 0
	s_setprio 1
	v_mfma_f32_16x16x32_bf16 v[116:119], v[162:165], v[178:181], v[116:119]
	v_mfma_f32_16x16x32_bf16 v[112:115], v[170:173], v[178:181], v[112:115]
	v_mfma_f32_16x16x32_bf16 v[100:103], v[162:165], v[186:189], v[100:103]
	v_mfma_f32_16x16x32_bf16 v[96:99], v[170:173], v[186:189], v[96:99]
	v_mfma_f32_16x16x32_bf16 v[84:87], v[162:165], v[210:213], v[84:87]
	v_mfma_f32_16x16x32_bf16 v[80:83], v[170:173], v[210:213], v[80:83]
	v_mfma_f32_16x16x32_bf16 v[68:71], v[162:165], v[218:221], v[68:71]
	v_mfma_f32_16x16x32_bf16 v[64:67], v[170:173], v[218:221], v[64:67]
	v_mfma_f32_16x16x32_bf16 v[116:119], v[166:169], v[182:185], v[116:119]
	v_mfma_f32_16x16x32_bf16 v[112:115], v[174:177], v[182:185], v[112:115]
	v_mfma_f32_16x16x32_bf16 v[100:103], v[166:169], v[206:209], v[100:103]
	v_mfma_f32_16x16x32_bf16 v[96:99], v[174:177], v[206:209], v[96:99]
	v_mfma_f32_16x16x32_bf16 v[84:87], v[166:169], v[214:217], v[84:87]
	v_mfma_f32_16x16x32_bf16 v[80:83], v[174:177], v[214:217], v[80:83]
	v_mfma_f32_16x16x32_bf16 v[68:71], v[166:169], v[222:225], v[68:71]
	v_mfma_f32_16x16x32_bf16 v[64:67], v[174:177], v[222:225], v[64:67]
	s_setprio 0
	s_barrier
	s_add_i32 s10, s12, s7
	s_add_i32 m0, s10, 0xffffff80
	ds_read_b128 v[178:181], v149 offset:49152
	ds_read_b128 v[182:185], v149 offset:50176
	ds_read_b128 v[186:189], v149 offset:51200
	ds_read_b128 v[206:209], v149 offset:52224
	ds_read_b128 v[210:213], v149 offset:53248
	ds_read_b128 v[214:217], v149 offset:54272
	ds_read_b128 v[218:221], v149 offset:55296
	ds_read_b128 v[222:225], v149 offset:56320
	global_load_lds_dwordx4 v192, s[62:63] offset:128
	s_add_i32 m0, s10, 0x1f80
	s_add_u32 s10, s62, 0x40080
	s_addc_u32 s11, s63, 0
	s_add_i32 s12, s13, s7
	global_load_lds_dwordx4 v132, s[62:63] offset:128
	s_mov_b32 m0, s12
	s_nop 0
	global_load_lds_dwordx4 v192, s[10:11]
	s_add_i32 m0, s12, 0x2000
	s_nop 0
	global_load_lds_dwordx4 v132, s[10:11]
	s_waitcnt vmcnt(6)
	s_waitcnt lgkmcnt(0)
	s_barrier
	s_setprio 1
	s_waitcnt lgkmcnt(0)
	v_mfma_f32_16x16x32_bf16 v[60:63], v[138:141], v[178:181], v[60:63]
	v_mfma_f32_16x16x32_bf16 v[56:59], v[154:157], v[178:181], v[56:59]
	v_mfma_f32_16x16x32_bf16 v[44:47], v[138:141], v[186:189], v[44:47]
	v_mfma_f32_16x16x32_bf16 v[40:43], v[154:157], v[186:189], v[40:43]
	v_mfma_f32_16x16x32_bf16 v[28:31], v[138:141], v[210:213], v[28:31]
	v_mfma_f32_16x16x32_bf16 v[24:27], v[154:157], v[210:213], v[24:27]
	v_mfma_f32_16x16x32_bf16 v[12:15], v[138:141], v[218:221], v[12:15]
	v_mfma_f32_16x16x32_bf16 v[8:11], v[154:157], v[218:221], v[8:11]
	v_mfma_f32_16x16x32_bf16 v[60:63], v[150:153], v[182:185], v[60:63]
	v_mfma_f32_16x16x32_bf16 v[56:59], v[158:161], v[182:185], v[56:59]
	v_mfma_f32_16x16x32_bf16 v[44:47], v[150:153], v[206:209], v[44:47]
	v_mfma_f32_16x16x32_bf16 v[40:43], v[158:161], v[206:209], v[40:43]
	v_mfma_f32_16x16x32_bf16 v[28:31], v[150:153], v[214:217], v[28:31]
	v_mfma_f32_16x16x32_bf16 v[24:27], v[158:161], v[214:217], v[24:27]
	v_mfma_f32_16x16x32_bf16 v[12:15], v[150:153], v[222:225], v[12:15]
	v_mfma_f32_16x16x32_bf16 v[8:11], v[158:161], v[222:225], v[8:11]
	s_setprio 0
	s_setprio 1
	v_mfma_f32_16x16x32_bf16 v[52:55], v[162:165], v[178:181], v[52:55]
	v_mfma_f32_16x16x32_bf16 v[48:51], v[170:173], v[178:181], v[48:51]
	v_mfma_f32_16x16x32_bf16 v[36:39], v[162:165], v[186:189], v[36:39]
	v_mfma_f32_16x16x32_bf16 v[32:35], v[170:173], v[186:189], v[32:35]
	v_mfma_f32_16x16x32_bf16 v[20:23], v[162:165], v[210:213], v[20:23]
	v_mfma_f32_16x16x32_bf16 v[16:19], v[170:173], v[210:213], v[16:19]
	v_mfma_f32_16x16x32_bf16 v[4:7], v[162:165], v[218:221], v[4:7]
	v_mfma_f32_16x16x32_bf16 v[0:3], v[170:173], v[218:221], v[0:3]
	v_mfma_f32_16x16x32_bf16 v[52:55], v[166:169], v[182:185], v[52:55]
	v_mfma_f32_16x16x32_bf16 v[48:51], v[174:177], v[182:185], v[48:51]
	v_mfma_f32_16x16x32_bf16 v[36:39], v[166:169], v[206:209], v[36:39]
	v_mfma_f32_16x16x32_bf16 v[32:35], v[174:177], v[206:209], v[32:35]
	v_mfma_f32_16x16x32_bf16 v[20:23], v[166:169], v[214:217], v[20:23]
	v_mfma_f32_16x16x32_bf16 v[16:19], v[174:177], v[214:217], v[16:19]
	v_mfma_f32_16x16x32_bf16 v[4:7], v[166:169], v[222:225], v[4:7]
	v_mfma_f32_16x16x32_bf16 v[0:3], v[174:177], v[222:225], v[0:3]
	s_setprio 0
	s_barrier
	s_add_i32 s96, s96, 2
	s_add_u32 s60, s60, 0x100
	s_addc_u32 s61, s61, 0
	s_add_u32 s83, s83, 0x100
	s_addc_u32 s95, s95, 0
	s_cmp_gt_u32 s96, 13
	s_cbranch_scc0 .LBB0_1039
	s_and_b64 vcc, exec, s[46:47]
	s_cbranch_vccz .LBB0_1042
	s_barrier

.LBB0_1144:
	s_add_u32 s10, s30, 0xfffc0080
	s_addc_u32 s11, s31, -1
	s_add_i32 s12, 0, 0x10000
	s_cmp_eq_u32 s47, 12
	s_cselect_b32 s55, s5, s11
	s_cselect_b32 s54, s6, s10
	v_add_u32_e32 v146, s12, v150
	s_cselect_b32 s41, s7, s23
	s_cselect_b32 s40, s8, s9
	s_add_i32 s13, 0, 0x14000
	ds_read_b128 v[138:141], v146
	ds_read_b128 v[142:145], v146 offset:1024
	ds_read_b128 v[154:157], v146 offset:2048
	ds_read_b128 v[158:161], v146 offset:3072
	v_add_u32_e32 v146, s13, v150
	ds_read_b128 v[162:165], v146
	ds_read_b128 v[166:169], v146 offset:1024
	ds_read_b128 v[170:173], v146 offset:2048
	ds_read_b128 v[174:177], v146 offset:3072
	s_add_u32 s10, s30, 0xfffc0000
	s_addc_u32 s11, s31, -1
	s_mov_b32 m0, s26
	s_nop 0
	global_load_lds_dwordx4 v134, s[10:11]
	s_mov_b32 m0, s67
	s_nop 0
	global_load_lds_dwordx4 v136, s[10:11]
	s_add_i32 m0, s63, 0xc000
	ds_read_b128 v[178:181], v152
	ds_read_b128 v[182:185], v152 offset:1024
	ds_read_b128 v[186:189], v152 offset:2048
	ds_read_b128 v[206:209], v152 offset:3072
	ds_read_b128 v[210:213], v152 offset:4096
	ds_read_b128 v[214:217], v152 offset:5120
	ds_read_b128 v[218:221], v152 offset:6144
	ds_read_b128 v[222:225], v152 offset:7168
	global_load_lds_dwordx4 v134, s[30:31]
	s_add_i32 m0, s63, 0xe000
	s_nop 0
	global_load_lds_dwordx4 v136, s[30:31]
	s_waitcnt vmcnt(8)
	s_waitcnt lgkmcnt(0)
	s_barrier
	s_setprio 1
	s_waitcnt lgkmcnt(0)
	v_mfma_f32_16x16x32_bf16 v[124:127], v[138:141], v[178:181], v[124:127]
	v_mfma_f32_16x16x32_bf16 v[120:123], v[154:157], v[178:181], v[120:123]
	v_mfma_f32_16x16x32_bf16 v[108:111], v[138:141], v[186:189], v[108:111]
	v_mfma_f32_16x16x32_bf16 v[104:107], v[154:157], v[186:189], v[104:107]
	v_mfma_f32_16x16x32_bf16 v[92:95], v[138:141], v[210:213], v[92:95]
	v_mfma_f32_16x16x32_bf16 v[88:91], v[154:157], v[210:213], v[88:91]
	v_mfma_f32_16x16x32_bf16 v[76:79], v[138:141], v[218:221], v[76:79]
	v_mfma_f32_16x16x32_bf16 v[72:75], v[154:157], v[218:221], v[72:75]
	v_mfma_f32_16x16x32_bf16 v[124:127], v[142:145], v[182:185], v[124:127]
	v_mfma_f32_16x16x32_bf16 v[120:123], v[158:161], v[182:185], v[120:123]
	v_mfma_f32_16x16x32_bf16 v[108:111], v[142:145], v[206:209], v[108:111]
	v_mfma_f32_16x16x32_bf16 v[104:107], v[158:161], v[206:209], v[104:107]
	v_mfma_f32_16x16x32_bf16 v[92:95], v[142:145], v[214:217], v[92:95]
	v_mfma_f32_16x16x32_bf16 v[88:91], v[158:161], v[214:217], v[88:91]
	v_mfma_f32_16x16x32_bf16 v[76:79], v[142:145], v[222:225], v[76:79]
	v_mfma_f32_16x16x32_bf16 v[72:75], v[158:161], v[222:225], v[72:75]
	s_setprio 0
	s_setprio 1
	v_mfma_f32_16x16x32_bf16 v[116:119], v[162:165], v[178:181], v[116:119]
	v_mfma_f32_16x16x32_bf16 v[112:115], v[170:173], v[178:181], v[112:115]
	v_mfma_f32_16x16x32_bf16 v[100:103], v[162:165], v[186:189], v[100:103]
	v_mfma_f32_16x16x32_bf16 v[96:99], v[170:173], v[186:189], v[96:99]
	v_mfma_f32_16x16x32_bf16 v[84:87], v[162:165], v[210:213], v[84:87]
	v_mfma_f32_16x16x32_bf16 v[80:83], v[170:173], v[210:213], v[80:83]
	v_mfma_f32_16x16x32_bf16 v[68:71], v[162:165], v[218:221], v[68:71]
	v_mfma_f32_16x16x32_bf16 v[64:67], v[170:173], v[218:221], v[64:67]
	v_mfma_f32_16x16x32_bf16 v[116:119], v[166:169], v[182:185], v[116:119]
	v_mfma_f32_16x16x32_bf16 v[112:115], v[174:177], v[182:185], v[112:115]
	v_mfma_f32_16x16x32_bf16 v[100:103], v[166:169], v[206:209], v[100:103]
	v_mfma_f32_16x16x32_bf16 v[96:99], v[174:177], v[206:209], v[96:99]
	v_mfma_f32_16x16x32_bf16 v[84:87], v[166:169], v[214:217], v[84:87]
	v_mfma_f32_16x16x32_bf16 v[80:83], v[174:177], v[214:217], v[80:83]
	v_mfma_f32_16x16x32_bf16 v[68:71], v[166:169], v[222:225], v[68:71]
	v_mfma_f32_16x16x32_bf16 v[64:67], v[174:177], v[222:225], v[64:67]
	s_setprio 0
	s_barrier
	s_add_i32 s10, s12, s62
	s_mov_b32 m0, s10
	ds_read_b128 v[178:181], v152 offset:16384
	ds_read_b128 v[182:185], v152 offset:17408
	ds_read_b128 v[186:189], v152 offset:18432
	ds_read_b128 v[206:209], v152 offset:19456
	ds_read_b128 v[210:213], v152 offset:20480
	ds_read_b128 v[214:217], v152 offset:21504
	ds_read_b128 v[218:221], v152 offset:22528
	ds_read_b128 v[222:225], v152 offset:23552
	global_load_lds_dwordx4 v192, s[40:41]
	s_add_i32 m0, s10, 0x2000
	s_add_u32 s10, s40, 0x40000
	s_addc_u32 s11, s41, 0
	s_add_i32 s12, s13, s62
	global_load_lds_dwordx4 v132, s[40:41]
	s_mov_b32 m0, s12
	s_nop 0
	global_load_lds_dwordx4 v192, s[10:11]
	s_add_i32 m0, s12, 0x2000
	s_nop 0
	global_load_lds_dwordx4 v132, s[10:11]
	s_waitcnt vmcnt(6)
	s_waitcnt lgkmcnt(0)
	s_barrier
	s_setprio 1
	s_waitcnt lgkmcnt(0)
	v_mfma_f32_16x16x32_bf16 v[60:63], v[138:141], v[178:181], v[60:63]
	v_mfma_f32_16x16x32_bf16 v[56:59], v[154:157], v[178:181], v[56:59]
	v_mfma_f32_16x16x32_bf16 v[44:47], v[138:141], v[186:189], v[44:47]
	v_mfma_f32_16x16x32_bf16 v[40:43], v[154:157], v[186:189], v[40:43]
	v_mfma_f32_16x16x32_bf16 v[28:31], v[138:141], v[210:213], v[28:31]
	v_mfma_f32_16x16x32_bf16 v[24:27], v[154:157], v[210:213], v[24:27]
	v_mfma_f32_16x16x32_bf16 v[12:15], v[138:141], v[218:221], v[12:15]
	v_mfma_f32_16x16x32_bf16 v[8:11], v[154:157], v[218:221], v[8:11]
	v_mfma_f32_16x16x32_bf16 v[60:63], v[142:145], v[182:185], v[60:63]
	v_mfma_f32_16x16x32_bf16 v[56:59], v[158:161], v[182:185], v[56:59]
	v_mfma_f32_16x16x32_bf16 v[44:47], v[142:145], v[206:209], v[44:47]
	v_mfma_f32_16x16x32_bf16 v[40:43], v[158:161], v[206:209], v[40:43]
	v_mfma_f32_16x16x32_bf16 v[28:31], v[142:145], v[214:217], v[28:31]
	v_mfma_f32_16x16x32_bf16 v[24:27], v[158:161], v[214:217], v[24:27]
	v_mfma_f32_16x16x32_bf16 v[12:15], v[142:145], v[222:225], v[12:15]
	v_mfma_f32_16x16x32_bf16 v[8:11], v[158:161], v[222:225], v[8:11]
	s_setprio 0
	s_setprio 1
	v_mfma_f32_16x16x32_bf16 v[52:55], v[162:165], v[178:181], v[52:55]
	v_mfma_f32_16x16x32_bf16 v[48:51], v[170:173], v[178:181], v[48:51]
	v_mfma_f32_16x16x32_bf16 v[36:39], v[162:165], v[186:189], v[36:39]
	v_mfma_f32_16x16x32_bf16 v[32:35], v[170:173], v[186:189], v[32:35]
	v_mfma_f32_16x16x32_bf16 v[20:23], v[162:165], v[210:213], v[20:23]
	v_mfma_f32_16x16x32_bf16 v[16:19], v[170:173], v[210:213], v[16:19]
	v_mfma_f32_16x16x32_bf16 v[4:7], v[162:165], v[218:221], v[4:7]
	v_mfma_f32_16x16x32_bf16 v[0:3], v[170:173], v[218:221], v[0:3]
	v_mfma_f32_16x16x32_bf16 v[52:55], v[166:169], v[182:185], v[52:55]
	v_mfma_f32_16x16x32_bf16 v[48:51], v[174:177], v[182:185], v[48:51]
	v_mfma_f32_16x16x32_bf16 v[36:39], v[166:169], v[206:209], v[36:39]
	v_mfma_f32_16x16x32_bf16 v[32:35], v[174:177], v[206:209], v[32:35]
	v_mfma_f32_16x16x32_bf16 v[20:23], v[166:169], v[214:217], v[20:23]
	v_mfma_f32_16x16x32_bf16 v[16:19], v[174:177], v[214:217], v[16:19]
	v_mfma_f32_16x16x32_bf16 v[4:7], v[166:169], v[222:225], v[4:7]
	v_mfma_f32_16x16x32_bf16 v[0:3], v[174:177], v[222:225], v[0:3]
	s_setprio 0
	s_barrier
	s_add_i32 s12, 0, 0x18000
	v_add_u32_e32 v146, s12, v150
	s_add_i32 s13, 0, 0x1c000
	ds_read_b128 v[138:141], v146
	ds_read_b128 v[142:145], v146 offset:1024
	ds_read_b128 v[154:157], v146 offset:2048
	ds_read_b128 v[158:161], v146 offset:3072
	v_add_u32_e32 v146, s13, v150
	ds_read_b128 v[162:165], v146
	ds_read_b128 v[166:169], v146 offset:1024
	ds_read_b128 v[170:173], v146 offset:2048
	ds_read_b128 v[174:177], v146 offset:3072
	s_mov_b32 m0, s63
	s_nop 0
	global_load_lds_dwordx4 v128, s[54:55]
	s_mov_b32 m0, s64
	s_nop 0
	global_load_lds_dwordx4 v130, s[54:55]
	s_add_u32 s10, s54, 0x40000
	s_addc_u32 s11, s55, 0
	s_mov_b32 m0, s65
	ds_read_b128 v[178:181], v152 offset:32768
	ds_read_b128 v[182:185], v152 offset:33792
	ds_read_b128 v[186:189], v152 offset:34816
	ds_read_b128 v[206:209], v152 offset:35840
	ds_read_b128 v[210:213], v152 offset:36864
	ds_read_b128 v[214:217], v152 offset:37888
	ds_read_b128 v[218:221], v152 offset:38912
	ds_read_b128 v[222:225], v152 offset:39936
	global_load_lds_dwordx4 v128, s[10:11]
	s_mov_b32 m0, s66
	s_nop 0
	global_load_lds_dwordx4 v130, s[10:11]
	s_waitcnt vmcnt(8)
	s_waitcnt lgkmcnt(0)
	s_barrier
	s_setprio 1
	s_waitcnt lgkmcnt(0)
	v_mfma_f32_16x16x32_bf16 v[124:127], v[138:141], v[178:181], v[124:127]
	v_mfma_f32_16x16x32_bf16 v[120:123], v[154:157], v[178:181], v[120:123]
	v_mfma_f32_16x16x32_bf16 v[108:111], v[138:141], v[186:189], v[108:111]
	v_mfma_f32_16x16x32_bf16 v[104:107], v[154:157], v[186:189], v[104:107]
	v_mfma_f32_16x16x32_bf16 v[92:95], v[138:141], v[210:213], v[92:95]
	v_mfma_f32_16x16x32_bf16 v[88:91], v[154:157], v[210:213], v[88:91]
	v_mfma_f32_16x16x32_bf16 v[76:79], v[138:141], v[218:221], v[76:79]
	v_mfma_f32_16x16x32_bf16 v[72:75], v[154:157], v[218:221], v[72:75]
	v_mfma_f32_16x16x32_bf16 v[124:127], v[142:145], v[182:185], v[124:127]
	v_mfma_f32_16x16x32_bf16 v[120:123], v[158:161], v[182:185], v[120:123]
	v_mfma_f32_16x16x32_bf16 v[108:111], v[142:145], v[206:209], v[108:111]
	v_mfma_f32_16x16x32_bf16 v[104:107], v[158:161], v[206:209], v[104:107]
	v_mfma_f32_16x16x32_bf16 v[92:95], v[142:145], v[214:217], v[92:95]
	v_mfma_f32_16x16x32_bf16 v[88:91], v[158:161], v[214:217], v[88:91]
	v_mfma_f32_16x16x32_bf16 v[76:79], v[142:145], v[222:225], v[76:79]
	v_mfma_f32_16x16x32_bf16 v[72:75], v[158:161], v[222:225], v[72:75]
	s_setprio 0
	s_setprio 1
	v_mfma_f32_16x16x32_bf16 v[116:119], v[162:165], v[178:181], v[116:119]
	v_mfma_f32_16x16x32_bf16 v[112:115], v[170:173], v[178:181], v[112:115]
	v_mfma_f32_16x16x32_bf16 v[100:103], v[162:165], v[186:189], v[100:103]
	v_mfma_f32_16x16x32_bf16 v[96:99], v[170:173], v[186:189], v[96:99]
	v_mfma_f32_16x16x32_bf16 v[84:87], v[162:165], v[210:213], v[84:87]
	v_mfma_f32_16x16x32_bf16 v[80:83], v[170:173], v[210:213], v[80:83]
	v_mfma_f32_16x16x32_bf16 v[68:71], v[162:165], v[218:221], v[68:71]
	v_mfma_f32_16x16x32_bf16 v[64:67], v[170:173], v[218:221], v[64:67]
	v_mfma_f32_16x16x32_bf16 v[116:119], v[166:169], v[182:185], v[116:119]
	v_mfma_f32_16x16x32_bf16 v[112:115], v[174:177], v[182:185], v[112:115]
	v_mfma_f32_16x16x32_bf16 v[100:103], v[166:169], v[206:209], v[100:103]
	v_mfma_f32_16x16x32_bf16 v[96:99], v[174:177], v[206:209], v[96:99]
	v_mfma_f32_16x16x32_bf16 v[84:87], v[166:169], v[214:217], v[84:87]
	v_mfma_f32_16x16x32_bf16 v[80:83], v[174:177], v[214:217], v[80:83]
	v_mfma_f32_16x16x32_bf16 v[68:71], v[166:169], v[222:225], v[68:71]
	v_mfma_f32_16x16x32_bf16 v[64:67], v[174:177], v[222:225], v[64:67]
	s_setprio 0
	s_barrier
	s_add_i32 s10, s12, s62
	s_add_i32 m0, s10, 0xffffff80
	ds_read_b128 v[178:181], v152 offset:49152
	ds_read_b128 v[182:185], v152 offset:50176
	ds_read_b128 v[186:189], v152 offset:51200
	ds_read_b128 v[206:209], v152 offset:52224
	ds_read_b128 v[210:213], v152 offset:53248
	ds_read_b128 v[214:217], v152 offset:54272
	ds_read_b128 v[218:221], v152 offset:55296
	ds_read_b128 v[222:225], v152 offset:56320
	global_load_lds_dwordx4 v192, s[40:41] offset:128
	s_add_i32 m0, s10, 0x1f80
	s_add_u32 s10, s40, 0x40080
	s_addc_u32 s11, s41, 0
	s_add_i32 s12, s13, s62
	global_load_lds_dwordx4 v132, s[40:41] offset:128
	s_mov_b32 m0, s12
	s_nop 0
	global_load_lds_dwordx4 v192, s[10:11]
	s_add_i32 m0, s12, 0x2000
	s_nop 0
	global_load_lds_dwordx4 v132, s[10:11]
	s_waitcnt vmcnt(6)
	s_waitcnt lgkmcnt(0)
	s_barrier
	s_setprio 1
	s_waitcnt lgkmcnt(0)
	v_mfma_f32_16x16x32_bf16 v[60:63], v[138:141], v[178:181], v[60:63]
	v_mfma_f32_16x16x32_bf16 v[56:59], v[154:157], v[178:181], v[56:59]
	v_mfma_f32_16x16x32_bf16 v[44:47], v[138:141], v[186:189], v[44:47]
	v_mfma_f32_16x16x32_bf16 v[40:43], v[154:157], v[186:189], v[40:43]
	v_mfma_f32_16x16x32_bf16 v[28:31], v[138:141], v[210:213], v[28:31]
	v_mfma_f32_16x16x32_bf16 v[24:27], v[154:157], v[210:213], v[24:27]
	v_mfma_f32_16x16x32_bf16 v[12:15], v[138:141], v[218:221], v[12:15]
	v_mfma_f32_16x16x32_bf16 v[8:11], v[154:157], v[218:221], v[8:11]
	v_mfma_f32_16x16x32_bf16 v[60:63], v[142:145], v[182:185], v[60:63]
	v_mfma_f32_16x16x32_bf16 v[56:59], v[158:161], v[182:185], v[56:59]
	v_mfma_f32_16x16x32_bf16 v[44:47], v[142:145], v[206:209], v[44:47]
	v_mfma_f32_16x16x32_bf16 v[40:43], v[158:161], v[206:209], v[40:43]
	v_mfma_f32_16x16x32_bf16 v[28:31], v[142:145], v[214:217], v[28:31]
	v_mfma_f32_16x16x32_bf16 v[24:27], v[158:161], v[214:217], v[24:27]
	v_mfma_f32_16x16x32_bf16 v[12:15], v[142:145], v[222:225], v[12:15]
	v_mfma_f32_16x16x32_bf16 v[8:11], v[158:161], v[222:225], v[8:11]
	s_setprio 0
	s_setprio 1
	v_mfma_f32_16x16x32_bf16 v[52:55], v[162:165], v[178:181], v[52:55]
	v_mfma_f32_16x16x32_bf16 v[48:51], v[170:173], v[178:181], v[48:51]
	v_mfma_f32_16x16x32_bf16 v[36:39], v[162:165], v[186:189], v[36:39]
	v_mfma_f32_16x16x32_bf16 v[32:35], v[170:173], v[186:189], v[32:35]
	v_mfma_f32_16x16x32_bf16 v[20:23], v[162:165], v[210:213], v[20:23]
	v_mfma_f32_16x16x32_bf16 v[16:19], v[170:173], v[210:213], v[16:19]
	v_mfma_f32_16x16x32_bf16 v[4:7], v[162:165], v[218:221], v[4:7]
	v_mfma_f32_16x16x32_bf16 v[0:3], v[170:173], v[218:221], v[0:3]
	v_mfma_f32_16x16x32_bf16 v[52:55], v[166:169], v[182:185], v[52:55]
	v_mfma_f32_16x16x32_bf16 v[48:51], v[174:177], v[182:185], v[48:51]
	v_mfma_f32_16x16x32_bf16 v[36:39], v[166:169], v[206:209], v[36:39]
	v_mfma_f32_16x16x32_bf16 v[32:35], v[174:177], v[206:209], v[32:35]
	v_mfma_f32_16x16x32_bf16 v[20:23], v[166:169], v[214:217], v[20:23]
	v_mfma_f32_16x16x32_bf16 v[16:19], v[174:177], v[214:217], v[16:19]
	v_mfma_f32_16x16x32_bf16 v[4:7], v[166:169], v[222:225], v[4:7]
	v_mfma_f32_16x16x32_bf16 v[0:3], v[174:177], v[222:225], v[0:3]
	s_setprio 0
	s_barrier
	s_add_i32 s47, s47, 2
	s_add_u32 s30, s30, 0x100
	s_addc_u32 s31, s31, 0
	s_add_u32 s9, s9, 0x100
	s_addc_u32 s23, s23, 0
	s_cmp_gt_u32 s47, 13
	s_cbranch_scc0 .LBB0_1144
	s_and_b64 vcc, exec, s[44:45]
	s_cbranch_vccz .LBB0_1147
	s_barrier

.LBB0_1229:
	s_add_u32 s10, s56, 0xfff00080
	s_addc_u32 s11, s57, -1
	s_add_i32 s12, 0, 0x10000
	s_cmp_eq_u32 s83, 60
	s_cselect_b32 s61, s47, s11
	s_cselect_b32 s60, s53, s10
	s_cselect_b32 s59, s45, s82
	s_cselect_b32 s58, s78, s79
	s_add_i32 s13, 0, 0x14000
	v_add_u32_e32 v156, s12, v145
	v_add_u32_e32 v172, s13, v145
	ds_read_b128 v[138:141], v156
	ds_read_b128 v[148:151], v156 offset:1024
	ds_read_b128 v[152:155], v156 offset:2048
	ds_read_b128 v[156:159], v156 offset:3072
	ds_read_b128 v[160:163], v172
	ds_read_b128 v[164:167], v172 offset:1024
	ds_read_b128 v[168:171], v172 offset:2048
	ds_read_b128 v[172:175], v172 offset:3072
	s_add_u32 s10, s56, 0xfff00000
	s_addc_u32 s11, s57, -1
	s_mov_b32 m0, s64
	s_nop 0
	global_load_lds_dwordx4 v134, s[10:11]
	s_mov_b32 m0, s65
	s_nop 0
	global_load_lds_dwordx4 v136, s[10:11]
	s_add_i32 m0, s9, 0xc000
	ds_read_b128 v[176:179], v147
	ds_read_b128 v[180:183], v147 offset:1024
	ds_read_b128 v[184:187], v147 offset:2048
	ds_read_b128 v[188:191], v147 offset:3072
	ds_read_b128 v[206:209], v147 offset:4096
	ds_read_b128 v[210:213], v147 offset:5120
	ds_read_b128 v[214:217], v147 offset:6144
	ds_read_b128 v[218:221], v147 offset:7168
	global_load_lds_dwordx4 v134, s[56:57]
	s_add_i32 m0, s9, 0xe000
	s_nop 0
	global_load_lds_dwordx4 v136, s[56:57]
	s_waitcnt vmcnt(8)
	s_waitcnt lgkmcnt(0)
	s_barrier
	s_setprio 1
	s_waitcnt lgkmcnt(0)
	v_mfma_f32_16x16x32_bf16 v[124:127], v[138:141], v[176:179], v[124:127]
	v_mfma_f32_16x16x32_bf16 v[120:123], v[152:155], v[176:179], v[120:123]
	v_mfma_f32_16x16x32_bf16 v[108:111], v[138:141], v[184:187], v[108:111]
	v_mfma_f32_16x16x32_bf16 v[104:107], v[152:155], v[184:187], v[104:107]
	v_mfma_f32_16x16x32_bf16 v[92:95], v[138:141], v[206:209], v[92:95]
	v_mfma_f32_16x16x32_bf16 v[88:91], v[152:155], v[206:209], v[88:91]
	v_mfma_f32_16x16x32_bf16 v[76:79], v[138:141], v[214:217], v[76:79]
	v_mfma_f32_16x16x32_bf16 v[72:75], v[152:155], v[214:217], v[72:75]
	v_mfma_f32_16x16x32_bf16 v[124:127], v[148:151], v[180:183], v[124:127]
	v_mfma_f32_16x16x32_bf16 v[120:123], v[156:159], v[180:183], v[120:123]
	v_mfma_f32_16x16x32_bf16 v[108:111], v[148:151], v[188:191], v[108:111]
	v_mfma_f32_16x16x32_bf16 v[104:107], v[156:159], v[188:191], v[104:107]
	v_mfma_f32_16x16x32_bf16 v[92:95], v[148:151], v[210:213], v[92:95]
	v_mfma_f32_16x16x32_bf16 v[88:91], v[156:159], v[210:213], v[88:91]
	v_mfma_f32_16x16x32_bf16 v[76:79], v[148:151], v[218:221], v[76:79]
	v_mfma_f32_16x16x32_bf16 v[72:75], v[156:159], v[218:221], v[72:75]
	s_setprio 0
	s_setprio 1
	v_mfma_f32_16x16x32_bf16 v[116:119], v[160:163], v[176:179], v[116:119]
	v_mfma_f32_16x16x32_bf16 v[112:115], v[168:171], v[176:179], v[112:115]
	v_mfma_f32_16x16x32_bf16 v[100:103], v[160:163], v[184:187], v[100:103]
	v_mfma_f32_16x16x32_bf16 v[96:99], v[168:171], v[184:187], v[96:99]
	v_mfma_f32_16x16x32_bf16 v[84:87], v[160:163], v[206:209], v[84:87]
	v_mfma_f32_16x16x32_bf16 v[80:83], v[168:171], v[206:209], v[80:83]
	v_mfma_f32_16x16x32_bf16 v[68:71], v[160:163], v[214:217], v[68:71]
	v_mfma_f32_16x16x32_bf16 v[64:67], v[168:171], v[214:217], v[64:67]
	v_mfma_f32_16x16x32_bf16 v[116:119], v[164:167], v[180:183], v[116:119]
	v_mfma_f32_16x16x32_bf16 v[112:115], v[172:175], v[180:183], v[112:115]
	v_mfma_f32_16x16x32_bf16 v[100:103], v[164:167], v[188:191], v[100:103]
	v_mfma_f32_16x16x32_bf16 v[96:99], v[172:175], v[188:191], v[96:99]
	v_mfma_f32_16x16x32_bf16 v[84:87], v[164:167], v[210:213], v[84:87]
	v_mfma_f32_16x16x32_bf16 v[80:83], v[172:175], v[210:213], v[80:83]
	v_mfma_f32_16x16x32_bf16 v[68:71], v[164:167], v[218:221], v[68:71]
	v_mfma_f32_16x16x32_bf16 v[64:67], v[172:175], v[218:221], v[64:67]
	s_setprio 0
	s_barrier
	s_add_i32 s10, s12, s8
	s_mov_b32 m0, s10
	ds_read_b128 v[176:179], v147 offset:16384
	ds_read_b128 v[180:183], v147 offset:17408
	ds_read_b128 v[184:187], v147 offset:18432
	ds_read_b128 v[188:191], v147 offset:19456
	ds_read_b128 v[206:209], v147 offset:20480
	ds_read_b128 v[210:213], v147 offset:21504
	ds_read_b128 v[214:217], v147 offset:22528
	ds_read_b128 v[218:221], v147 offset:23552
	global_load_lds_dwordx4 v192, s[58:59]
	s_add_i32 m0, s10, 0x2000
	s_add_u32 s10, s58, 0x100000
	s_addc_u32 s11, s59, 0
	s_add_i32 s12, s13, s8
	global_load_lds_dwordx4 v132, s[58:59]
	s_mov_b32 m0, s12
	s_nop 0
	global_load_lds_dwordx4 v192, s[10:11]
	s_add_i32 m0, s12, 0x2000
	s_nop 0
	global_load_lds_dwordx4 v132, s[10:11]
	s_waitcnt vmcnt(6)
	s_waitcnt lgkmcnt(0)
	s_barrier
	s_setprio 1
	s_waitcnt lgkmcnt(0)
	v_mfma_f32_16x16x32_bf16 v[60:63], v[138:141], v[176:179], v[60:63]
	v_mfma_f32_16x16x32_bf16 v[56:59], v[152:155], v[176:179], v[56:59]
	v_mfma_f32_16x16x32_bf16 v[44:47], v[138:141], v[184:187], v[44:47]
	v_mfma_f32_16x16x32_bf16 v[40:43], v[152:155], v[184:187], v[40:43]
	v_mfma_f32_16x16x32_bf16 v[28:31], v[138:141], v[206:209], v[28:31]
	v_mfma_f32_16x16x32_bf16 v[24:27], v[152:155], v[206:209], v[24:27]
	v_mfma_f32_16x16x32_bf16 v[12:15], v[138:141], v[214:217], v[12:15]
	v_mfma_f32_16x16x32_bf16 v[8:11], v[152:155], v[214:217], v[8:11]
	v_mfma_f32_16x16x32_bf16 v[60:63], v[148:151], v[180:183], v[60:63]
	v_mfma_f32_16x16x32_bf16 v[56:59], v[156:159], v[180:183], v[56:59]
	v_mfma_f32_16x16x32_bf16 v[44:47], v[148:151], v[188:191], v[44:47]
	v_mfma_f32_16x16x32_bf16 v[40:43], v[156:159], v[188:191], v[40:43]
	v_mfma_f32_16x16x32_bf16 v[28:31], v[148:151], v[210:213], v[28:31]
	v_mfma_f32_16x16x32_bf16 v[24:27], v[156:159], v[210:213], v[24:27]
	v_mfma_f32_16x16x32_bf16 v[12:15], v[148:151], v[218:221], v[12:15]
	v_mfma_f32_16x16x32_bf16 v[8:11], v[156:159], v[218:221], v[8:11]
	s_setprio 0
	s_setprio 1
	v_mfma_f32_16x16x32_bf16 v[52:55], v[160:163], v[176:179], v[52:55]
	v_mfma_f32_16x16x32_bf16 v[48:51], v[168:171], v[176:179], v[48:51]
	v_mfma_f32_16x16x32_bf16 v[36:39], v[160:163], v[184:187], v[36:39]
	v_mfma_f32_16x16x32_bf16 v[32:35], v[168:171], v[184:187], v[32:35]
	v_mfma_f32_16x16x32_bf16 v[20:23], v[160:163], v[206:209], v[20:23]
	v_mfma_f32_16x16x32_bf16 v[16:19], v[168:171], v[206:209], v[16:19]
	v_mfma_f32_16x16x32_bf16 v[4:7], v[160:163], v[214:217], v[4:7]
	v_mfma_f32_16x16x32_bf16 v[0:3], v[168:171], v[214:217], v[0:3]
	v_mfma_f32_16x16x32_bf16 v[52:55], v[164:167], v[180:183], v[52:55]
	v_mfma_f32_16x16x32_bf16 v[48:51], v[172:175], v[180:183], v[48:51]
	v_mfma_f32_16x16x32_bf16 v[36:39], v[164:167], v[188:191], v[36:39]
	v_mfma_f32_16x16x32_bf16 v[32:35], v[172:175], v[188:191], v[32:35]
	v_mfma_f32_16x16x32_bf16 v[20:23], v[164:167], v[210:213], v[20:23]
	v_mfma_f32_16x16x32_bf16 v[16:19], v[172:175], v[210:213], v[16:19]
	v_mfma_f32_16x16x32_bf16 v[4:7], v[164:167], v[218:221], v[4:7]
	v_mfma_f32_16x16x32_bf16 v[0:3], v[172:175], v[218:221], v[0:3]
	s_setprio 0
	s_barrier
	s_add_i32 s12, 0, 0x18000
	s_add_i32 s13, 0, 0x1c000
	v_add_u32_e32 v156, s12, v145
	v_add_u32_e32 v172, s13, v145
	ds_read_b128 v[138:141], v156
	ds_read_b128 v[148:151], v156 offset:1024
	ds_read_b128 v[152:155], v156 offset:2048
	ds_read_b128 v[156:159], v156 offset:3072
	ds_read_b128 v[160:163], v172
	ds_read_b128 v[164:167], v172 offset:1024
	ds_read_b128 v[168:171], v172 offset:2048
	ds_read_b128 v[172:175], v172 offset:3072
	s_mov_b32 m0, s9
	s_nop 0
	global_load_lds_dwordx4 v128, s[60:61]
	s_mov_b32 m0, s55
	s_nop 0
	global_load_lds_dwordx4 v130, s[60:61]
	s_add_u32 s10, s60, 0x100000
	s_addc_u32 s11, s61, 0
	s_mov_b32 m0, s62
	ds_read_b128 v[176:179], v147 offset:32768
	ds_read_b128 v[180:183], v147 offset:33792
	ds_read_b128 v[184:187], v147 offset:34816
	ds_read_b128 v[188:191], v147 offset:35840
	ds_read_b128 v[206:209], v147 offset:36864
	ds_read_b128 v[210:213], v147 offset:37888
	ds_read_b128 v[214:217], v147 offset:38912
	ds_read_b128 v[218:221], v147 offset:39936
	global_load_lds_dwordx4 v128, s[10:11]
	s_mov_b32 m0, s63
	s_nop 0
	global_load_lds_dwordx4 v130, s[10:11]
	s_waitcnt vmcnt(8)
	s_waitcnt lgkmcnt(0)
	s_barrier
	s_setprio 1
	s_waitcnt lgkmcnt(0)
	v_mfma_f32_16x16x32_bf16 v[124:127], v[138:141], v[176:179], v[124:127]
	v_mfma_f32_16x16x32_bf16 v[120:123], v[152:155], v[176:179], v[120:123]
	v_mfma_f32_16x16x32_bf16 v[108:111], v[138:141], v[184:187], v[108:111]
	v_mfma_f32_16x16x32_bf16 v[104:107], v[152:155], v[184:187], v[104:107]
	v_mfma_f32_16x16x32_bf16 v[92:95], v[138:141], v[206:209], v[92:95]
	v_mfma_f32_16x16x32_bf16 v[88:91], v[152:155], v[206:209], v[88:91]
	v_mfma_f32_16x16x32_bf16 v[76:79], v[138:141], v[214:217], v[76:79]
	v_mfma_f32_16x16x32_bf16 v[72:75], v[152:155], v[214:217], v[72:75]
	v_mfma_f32_16x16x32_bf16 v[124:127], v[148:151], v[180:183], v[124:127]
	v_mfma_f32_16x16x32_bf16 v[120:123], v[156:159], v[180:183], v[120:123]
	v_mfma_f32_16x16x32_bf16 v[108:111], v[148:151], v[188:191], v[108:111]
	v_mfma_f32_16x16x32_bf16 v[104:107], v[156:159], v[188:191], v[104:107]
	v_mfma_f32_16x16x32_bf16 v[92:95], v[148:151], v[210:213], v[92:95]
	v_mfma_f32_16x16x32_bf16 v[88:91], v[156:159], v[210:213], v[88:91]
	v_mfma_f32_16x16x32_bf16 v[76:79], v[148:151], v[218:221], v[76:79]
	v_mfma_f32_16x16x32_bf16 v[72:75], v[156:159], v[218:221], v[72:75]
	s_setprio 0
	s_setprio 1
	v_mfma_f32_16x16x32_bf16 v[116:119], v[160:163], v[176:179], v[116:119]
	v_mfma_f32_16x16x32_bf16 v[112:115], v[168:171], v[176:179], v[112:115]
	v_mfma_f32_16x16x32_bf16 v[100:103], v[160:163], v[184:187], v[100:103]
	v_mfma_f32_16x16x32_bf16 v[96:99], v[168:171], v[184:187], v[96:99]
	v_mfma_f32_16x16x32_bf16 v[84:87], v[160:163], v[206:209], v[84:87]
	v_mfma_f32_16x16x32_bf16 v[80:83], v[168:171], v[206:209], v[80:83]
	v_mfma_f32_16x16x32_bf16 v[68:71], v[160:163], v[214:217], v[68:71]
	v_mfma_f32_16x16x32_bf16 v[64:67], v[168:171], v[214:217], v[64:67]
	v_mfma_f32_16x16x32_bf16 v[116:119], v[164:167], v[180:183], v[116:119]
	v_mfma_f32_16x16x32_bf16 v[112:115], v[172:175], v[180:183], v[112:115]
	v_mfma_f32_16x16x32_bf16 v[100:103], v[164:167], v[188:191], v[100:103]
	v_mfma_f32_16x16x32_bf16 v[96:99], v[172:175], v[188:191], v[96:99]
	v_mfma_f32_16x16x32_bf16 v[84:87], v[164:167], v[210:213], v[84:87]
	v_mfma_f32_16x16x32_bf16 v[80:83], v[172:175], v[210:213], v[80:83]
	v_mfma_f32_16x16x32_bf16 v[68:71], v[164:167], v[218:221], v[68:71]
	v_mfma_f32_16x16x32_bf16 v[64:67], v[172:175], v[218:221], v[64:67]
	s_setprio 0
	s_barrier
	s_add_i32 s10, s12, s8
	s_add_i32 m0, s10, 0xffffff80
	ds_read_b128 v[176:179], v147 offset:49152
	ds_read_b128 v[180:183], v147 offset:50176
	ds_read_b128 v[184:187], v147 offset:51200
	ds_read_b128 v[188:191], v147 offset:52224
	ds_read_b128 v[206:209], v147 offset:53248
	ds_read_b128 v[210:213], v147 offset:54272
	ds_read_b128 v[214:217], v147 offset:55296
	ds_read_b128 v[218:221], v147 offset:56320
	global_load_lds_dwordx4 v192, s[58:59] offset:128
	s_add_i32 m0, s10, 0x1f80
	s_add_u32 s10, s58, 0x100080
	s_addc_u32 s11, s59, 0
	s_add_i32 s12, s13, s8
	global_load_lds_dwordx4 v132, s[58:59] offset:128
	s_mov_b32 m0, s12
	s_nop 0
	global_load_lds_dwordx4 v192, s[10:11]
	s_add_i32 m0, s12, 0x2000
	s_nop 0
	global_load_lds_dwordx4 v132, s[10:11]
	s_waitcnt vmcnt(6)
	s_waitcnt lgkmcnt(0)
	s_barrier
	s_setprio 1
	s_waitcnt lgkmcnt(0)
	v_mfma_f32_16x16x32_bf16 v[60:63], v[138:141], v[176:179], v[60:63]
	v_mfma_f32_16x16x32_bf16 v[56:59], v[152:155], v[176:179], v[56:59]
	v_mfma_f32_16x16x32_bf16 v[44:47], v[138:141], v[184:187], v[44:47]
	v_mfma_f32_16x16x32_bf16 v[40:43], v[152:155], v[184:187], v[40:43]
	v_mfma_f32_16x16x32_bf16 v[28:31], v[138:141], v[206:209], v[28:31]
	v_mfma_f32_16x16x32_bf16 v[24:27], v[152:155], v[206:209], v[24:27]
	v_mfma_f32_16x16x32_bf16 v[12:15], v[138:141], v[214:217], v[12:15]
	v_mfma_f32_16x16x32_bf16 v[8:11], v[152:155], v[214:217], v[8:11]
	v_mfma_f32_16x16x32_bf16 v[60:63], v[148:151], v[180:183], v[60:63]
	v_mfma_f32_16x16x32_bf16 v[56:59], v[156:159], v[180:183], v[56:59]
	v_mfma_f32_16x16x32_bf16 v[44:47], v[148:151], v[188:191], v[44:47]
	v_mfma_f32_16x16x32_bf16 v[40:43], v[156:159], v[188:191], v[40:43]
	v_mfma_f32_16x16x32_bf16 v[28:31], v[148:151], v[210:213], v[28:31]
	v_mfma_f32_16x16x32_bf16 v[24:27], v[156:159], v[210:213], v[24:27]
	v_mfma_f32_16x16x32_bf16 v[12:15], v[148:151], v[218:221], v[12:15]
	v_mfma_f32_16x16x32_bf16 v[8:11], v[156:159], v[218:221], v[8:11]
	s_setprio 0
	s_setprio 1
	v_mfma_f32_16x16x32_bf16 v[52:55], v[160:163], v[176:179], v[52:55]
	v_mfma_f32_16x16x32_bf16 v[48:51], v[168:171], v[176:179], v[48:51]
	v_mfma_f32_16x16x32_bf16 v[36:39], v[160:163], v[184:187], v[36:39]
	v_mfma_f32_16x16x32_bf16 v[32:35], v[168:171], v[184:187], v[32:35]
	v_mfma_f32_16x16x32_bf16 v[20:23], v[160:163], v[206:209], v[20:23]
	v_mfma_f32_16x16x32_bf16 v[16:19], v[168:171], v[206:209], v[16:19]
	v_mfma_f32_16x16x32_bf16 v[4:7], v[160:163], v[214:217], v[4:7]
	v_mfma_f32_16x16x32_bf16 v[0:3], v[168:171], v[214:217], v[0:3]
	v_mfma_f32_16x16x32_bf16 v[52:55], v[164:167], v[180:183], v[52:55]
	v_mfma_f32_16x16x32_bf16 v[48:51], v[172:175], v[180:183], v[48:51]
	v_mfma_f32_16x16x32_bf16 v[36:39], v[164:167], v[188:191], v[36:39]
	v_mfma_f32_16x16x32_bf16 v[32:35], v[172:175], v[188:191], v[32:35]
	v_mfma_f32_16x16x32_bf16 v[20:23], v[164:167], v[210:213], v[20:23]
	v_mfma_f32_16x16x32_bf16 v[16:19], v[172:175], v[210:213], v[16:19]
	v_mfma_f32_16x16x32_bf16 v[4:7], v[164:167], v[218:221], v[4:7]
	v_mfma_f32_16x16x32_bf16 v[0:3], v[172:175], v[218:221], v[0:3]
	s_setprio 0
	s_barrier
	s_add_i32 s83, s83, 2
	s_add_u32 s56, s56, 0x100
	s_addc_u32 s57, s57, 0
	s_add_u32 s79, s79, 0x100
	s_addc_u32 s82, s82, 0
	s_cmp_gt_u32 s83, 61
	s_cbranch_scc0 .LBB0_1229
	s_and_b64 vcc, exec, s[42:43]
	s_cbranch_vccz .LBB0_1232
	s_barrier
